# dilated attention: band bias/mask from a NEGBIG-padded LDS table (16 plain reads instead of 16 exec-masked lookups)
# speedup vs baseline: 1.0244x; 1.0029x over previous
; #define LAS __attribute__((address_space(3)))
; #define DL_LOAD(j0_) do { if ((j0_) >= 0 && (j0_) < L) { _Pragma("unroll") for (int i = 0; i < 4; ++i) { const bf16* sp = sKb + (size_t)((j0_) + rowK + 16 * i) * dil * 1536; gk[i] = *(const v4u*)sp; gv[i] = *(const v4u*)(sp + (size_t)T * (OFF_LV - OFF_LK)); } } } while (0)
; __device__ __forceinline__ void dil_item(const Params& p, LAS unsigned char* lds, const int bitem) {
;     int tid_l = threadIdx.x; asm volatile("" : "+v"(tid_l));
;     const int tid = tid_l, lane = tid & 63, wave = tid >> 6, r = lane & 31, h = lane >> 5, sub = wave >> 2, wq = wave & 3, ht = tid & 255;
;     const int sid = 2 * bitem + sub, g = sid >> 9, rem = sid & 511;
;     const int sh = 2 * g, dil = 1 << sh, L = 2048 >> sh, nI = L >> 7;
;     const int ii = rem % nI, cls = (rem / nI) & (dil - 1), hh = (rem >> 4) & 3, b = rem >> 6;
;     const bf16* Z = (const bf16*)(p.ws + WS_Z);
;     bf16* OG = (bf16*)(p.ws + WS_OG) + (size_t)g * T * 512; float* LSE = (float*)(p.ws + WS_LSE) + (size_t)g * T * 4;
;     const float* gtab = (const float*)(p.ws + WS_TAB) + 65536 + (g * 4 + hh) * 132;
;     LAS unsigned char* base = lds + sub * DL_SUB;
;     LAS float* tab = (LAS float*)(lds + DL_TAB) + sub * 132;
;     const int jq0 = 128 * ii + 32 * wq, jq = jq0 + r;
;     const size_t tq = (size_t)b * 2048 + (size_t)jq * dil + cls;
;     __syncthreads();
;     if (ht < 129) tab[ht] = gtab[ht];
;     v8s Q[1][8];
; #pragma unroll
;     for (int ks = 0; ks < 8; ++ks) Q[0][ks] = *(const v8s*)(Z + (size_t)T * OFF_LQ + tq * 1536 + g * 512 + hh * 128 + ks * 16 + h * 8);
;     AttnAcc<1> st; attn_init<1>(st);
;     const int rowK = ht >> 4, ccK = ht & 15;
;     const bf16* sKb = Z + (size_t)T * OFF_LK + ((size_t)b * 2048 + cls) * 1536 + g * 512 + hh * 128 + ccK * 8;
;     LAS unsigned char* dK = base + DL_K + rowK * 272 + ccK * 16; LAS unsigned char* dV = base + DL_VT + rowK * 320 + ccK * 16;
;     const int jbase = 128 * ii - 64;
;     const float c1 = 0.08838834764831845f * LOG2E;
;     v4u gk[4], gv[4];
;     ...
;     DL_LOAD(jbase);
.LBB0_158:
	v_mov_b32_e32 v2, v204
	s_lshl_b32 s6, s50, 1
	s_addk_i32 s6, 0xfe00
	v_ashrrev_i32_e32 v3, 8, v2
	v_add_u32_e32 v7, s6, v3
	v_readlane_b32 s6, v250, 10
	v_ashrrev_i32_e32 v146, 9, v7
	v_bfe_u32 v173, v7, 4, 2
	v_mov_b32_e32 v0, s6
	s_movk_i32 s6, 0x210
	v_lshlrev_b32_e32 v147, 10, v3
	v_add_u32_e32 v147, 0x12d20, v147
	s_movk_i32 s6, 0x81
	v_and_b32_e32 v0, 0xff, v2
	v_subrev_u32_e32 v0, 64, v0
	v_cmp_gt_u32_e64 s[10:11], s6, v0
	v_mov_b32_e32 v4, 0xf149f2ca
	s_barrier
	s_and_saveexec_b64 s[6:7], s[10:11]
	s_cbranch_execz .LBB0_160
	v_lshl_or_b32 v0, v146, 2, v173
	s_movk_i32 s10, 0x84
	v_mul_lo_u32 v4, v0, s10
	v_readlane_b32 s10, v249, 30
	v_ashrrev_i32_e32 v5, 31, v4
	v_readlane_b32 s11, v249, 31
	v_and_b32_e32 v0, 0xff, v2
	v_subrev_u32_e32 v0, 64, v0
	v_lshlrev_b32_e32 v0, 2, v0
	s_nop 0
	v_lshl_add_u64 v[4:5], v[4:5], 2, s[10:11]
	v_lshl_add_u64 v[4:5], v[4:5], 0, v[0:1]
	global_load_dword v4, v[4:5], off
.LBB0_160:
	s_or_b64 exec, exec, s[6:7]
	v_and_b32_e32 v0, 0xff, v2
	v_lshl_add_u32 v0, v0, 2, v147
	v_add_u32_e32 v0, 0xffffff00, v0
	s_waitcnt vmcnt(0)
	ds_write_b32 v0, v4
	v_lshlrev_b32_e32 v180, 1, v146
	v_lshrrev_b32_e64 v5, v180, 16
	v_add_u32_e32 v5, -1, v5
	s_movk_i32 s6, 0x1ff
	v_ashrrev_i32_e32 v182, 6, v2
	v_and_b32_e32 v0, 0x1ff, v7
	v_bitop3_b32 v16, v5, v7, s6 bitop3:0x80
	v_sub_u32_e32 v5, 4, v180
	v_lshrrev_b32_e32 v10, v5, v0
	v_lshlrev_b32_e32 v0, 5, v182
	v_lshlrev_b32_e32 v152, 7, v16
	v_and_b32_e32 v5, 0x60, v0
	v_and_b32_e32 v4, 31, v2
	v_or_b32_e32 v181, v152, v5
	v_lshlrev_b32_e32 v8, 5, v7
	v_lshlrev_b32_e64 v11, v180, -1
	v_or_b32_e32 v0, v181, v4
	v_and_b32_e32 v12, 0x3800, v8
	v_readlane_b32 s6, v249, 32
	v_lshlrev_b64 v[8:9], v180, v[0:1]
	v_bitop3_b32 v0, v10, v12, v11 bitop3:0xdc
	v_readlane_b32 s7, v249, 33
	v_lshl_add_u64 v[148:149], v[8:9], 0, v[0:1]
	v_bfe_u32 v6, v2, 5, 1
	v_mov_b64_e32 v[8:9], s[6:7]
	v_mad_u64_u32 v[8:9], s[6:7], v148, s24, v[8:9]
	v_mov_b32_e32 v10, v9
	v_mad_u64_u32 v[10:11], s[6:7], v149, s24, v[10:11]
	v_mov_b32_e32 v9, v10
	v_and_b32_e32 v10, 0xfffffe00, v7
	v_ashrrev_i32_e32 v11, 31, v10
	v_lshlrev_b64 v[10:11], 1, v[10:11]
	v_lshl_add_u64 v[8:9], v[8:9], 0, v[10:11]
	v_lshlrev_b32_e32 v12, 8, v173
	v_mov_b32_e32 v13, v1
	v_lshl_add_u64 v[8:9], v[8:9], 0, v[12:13]
	v_lshlrev_b32_e32 v14, 4, v6
	v_mov_b32_e32 v15, v1
	v_lshl_add_u64 v[8:9], v[8:9], 0, v[14:15]
	global_load_dwordx4 v[82:85], v[8:9], off
	global_load_dwordx4 v[86:89], v[8:9], off offset:32
	global_load_dwordx4 v[90:93], v[8:9], off offset:64
	global_load_dwordx4 v[94:97], v[8:9], off offset:96
	global_load_dwordx4 v[98:101], v[8:9], off offset:128
	global_load_dwordx4 v[102:105], v[8:9], off offset:160
	global_load_dwordx4 v[106:109], v[8:9], off offset:192
	global_load_dwordx4 v[110:113], v[8:9], off offset:224
	s_movk_i32 s6, 0x800
	v_lshrrev_b32_e64 v185, v180, s6
	v_readlane_b32 s6, v249, 34
	v_readlane_b32 s7, v249, 35
	v_and_b32_e32 v8, 15, v2
	v_subrev_u32_e32 v9, 64, v152
	v_mov_b64_e32 v[14:15], s[6:7]
	v_mad_u64_u32 v[14:15], s[6:7], v0, s24, v[14:15]
	v_lshl_add_u64 v[10:11], v[14:15], 0, v[10:11]
	v_lshl_add_u64 v[10:11], v[10:11], 0, v[12:13]
	v_lshlrev_b32_e32 v150, 4, v8
	v_mov_b32_e32 v151, v1
	v_cmp_ne_u32_e32 vcc, 0, v16
	v_cmp_lt_i32_e64 s[38:39], v9, v185
	v_lshrrev_b32_sdwa v7, v211, v2 dst_sel:DWORD dst_unused:UNUSED_PAD src0_sel:DWORD src1_sel:BYTE_0
	v_lshl_add_u64 v[154:155], v[10:11], 0, v[150:151]
	s_and_b64 s[10:11], vcc, s[38:39]
	s_and_saveexec_b64 s[6:7], s[10:11]
	s_cbranch_execz .LBB0_162
	v_or_b32_e32 v10, v9, v7
	v_ashrrev_i32_e32 v11, 31, v10
	v_lshlrev_b64 v[12:13], v180, v[10:11]
	v_mad_u64_u32 v[14:15], s[10:11], v12, s24, v[154:155]
	v_mov_b32_e32 v12, v15
	v_mad_u64_u32 v[12:13], s[10:11], v13, s24, v[12:13]
	v_add_co_u32_e32 v16, vcc, s25, v14
	v_mov_b32_e32 v15, v12
	s_nop 0
	v_addc_co_u32_e32 v17, vcc, 0, v12, vcc
	v_or_b32_e32 v12, 16, v10
	v_ashrrev_i32_e32 v13, 31, v12
	v_lshlrev_b64 v[12:13], v180, v[12:13]
	v_mad_u64_u32 v[18:19], s[10:11], v12, s24, v[154:155]
	v_mov_b32_e32 v12, v19
	v_mad_u64_u32 v[12:13], s[10:11], v13, s24, v[12:13]
	v_mov_b32_e32 v19, v12
	global_load_dwordx4 v[114:117], v[14:15], off
	global_load_dwordx4 v[118:121], v[18:19], off
	v_add_co_u32_e32 v14, vcc, s25, v18
	s_nop 1
	v_addc_co_u32_e32 v15, vcc, 0, v12, vcc
	v_or_b32_e32 v12, 32, v10
	v_ashrrev_i32_e32 v13, 31, v12
	v_lshlrev_b64 v[12:13], v180, v[12:13]
	global_load_dwordx4 v[122:125], v[16:17], off
	global_load_dwordx4 v[126:129], v[14:15], off
	v_mad_u64_u32 v[14:15], s[10:11], v12, s24, v[154:155]
	v_or_b32_e32 v10, 48, v10
	v_mov_b32_e32 v12, v15
	v_ashrrev_i32_e32 v11, 31, v10
	v_mad_u64_u32 v[12:13], s[10:11], v13, s24, v[12:13]
	v_add_co_u32_e32 v16, vcc, s25, v14
	v_lshlrev_b64 v[10:11], v180, v[10:11]
	v_mov_b32_e32 v15, v12
	v_addc_co_u32_e32 v17, vcc, 0, v12, vcc
	v_mad_u64_u32 v[12:13], s[10:11], v10, s24, v[154:155]
	v_mov_b32_e32 v10, v13
	v_mad_u64_u32 v[10:11], s[10:11], v11, s24, v[10:11]
	v_mov_b32_e32 v13, v10
	global_load_dwordx4 v[130:133], v[14:15], off
	global_load_dwordx4 v[134:137], v[12:13], off
	v_add_co_u32_e32 v12, vcc, 0x3000000, v12
	s_nop 1
	v_addc_co_u32_e32 v13, vcc, 0, v10, vcc
	global_load_dwordx4 v[138:141], v[16:17], off
	global_load_dwordx4 v[142:145], v[12:13], off

; #define LAS __attribute__((address_space(3)))
; #define MFMA32(a, b, c) __builtin_amdgcn_mfma_f32_32x32x16_bf16((a), (b), (c), 0, 0, 0)
; template <int D, int NM, int KSTR, int VSTR, bool QLDS, class BF> ...
;     v8s P[NM][2];
; #pragma unroll
;     for (int m = 0; m < NM; ++m) {
;         const LAS unsigned char* Kb = (m == 0 ? K0 : K1) + (32 * kk + r) * KSTR + h * 16;
;         v16f S;
; #pragma unroll
;         for (int i = 0; i < 16; ++i) S[i] = 0.f;
;         v8s kfa[D / 16];
; #pragma unroll
;         for (int ks = 0; ks < D / 16; ++ks) kfa[ks] = *(const LAS v8s*)(Kb + ks * 32);
;         __builtin_amdgcn_sched_barrier(0);
; #pragma unroll
;         for (int ks = 0; ks < D / 16; ++ks) { const v8s qf = QLDS ? *(const LAS v8s*)(qlds + (m * (D / 16) + ks) * 1024) : Q[m][ks]; S = MFMA32(kfa[ks], qf, S); }
;         __builtin_amdgcn_sched_barrier(0);
;         float tmax = NEGBIG;
; #pragma unroll
;         for (int i = 0; i < 16; ++i) { S[i] = S[i] * c1 + bias(i); tmax = fmaxf(tmax, S[i]); }
; __device__ __forceinline__ void dil_item(const Params& p, LAS unsigned char* lds, const int bitem) {
;     ...
;             for (int kk = 0; kk < 2; ++kk) {
;                 const int js = j0 + 32 * kk;
;                 if (js + 31 >= jq0 - 64 && js <= jq0 + 31 + 64) {
;                     const BiasBand bf{tab, js + 4 * h - jq};
;                     attn_subtile<128, 1, 272, 320, false>(base + DL_K, base + DL_K, base + DL_VT, kk, Q, nullptr, st, c1, bf, r, h);
.LBB0_172:
	s_and_saveexec_b64 s[18:19], s[10:11]
	s_cbranch_execz .LBB0_165
	v_subrev_u32_e32 v67, 33, v176
	v_cmp_ge_i32_e32 vcc, v67, v188
	v_cmp_le_i32_e64 s[38:39], v66, v189
	s_and_b64 s[10:11], vcc, s[38:39]
	s_and_saveexec_b64 s[20:21], s[10:11]
	s_cbranch_execz .LBB0_209
	v_add_u32_e32 v70, v190, v187
	ds_read_b128 v[66:69], v70
	ds_read_b128 v[198:201], v70 offset:32
	ds_read_b128 v[216:219], v70 offset:64
	ds_read_b128 v[220:223], v70 offset:96
	ds_read_b128 v[224:227], v70 offset:128
	ds_read_b128 v[228:231], v70 offset:160
	ds_read_b128 v[232:235], v70 offset:192
	ds_read_b128 v[236:239], v70 offset:224
	v_lshl_add_u64 v[178:179], v[174:175], 0, s[6:7]
	v_subrev_u32_e32 v197, 64, v178
	s_waitcnt lgkmcnt(7)
	v_mfma_f32_32x32x16_bf16 v[66:81], v[66:69], v[82:85], 0
	s_waitcnt lgkmcnt(6)
	v_mfma_f32_32x32x16_bf16 v[66:81], v[198:201], v[86:89], v[66:81]
	s_waitcnt lgkmcnt(5)
	v_mfma_f32_32x32x16_bf16 v[66:81], v[216:219], v[90:93], v[66:81]
	s_waitcnt lgkmcnt(4)
	v_mfma_f32_32x32x16_bf16 v[66:81], v[220:223], v[94:97], v[66:81]
	s_waitcnt lgkmcnt(3)
	v_mfma_f32_32x32x16_bf16 v[66:81], v[224:227], v[98:101], v[66:81]
	s_waitcnt lgkmcnt(2)
	v_mfma_f32_32x32x16_bf16 v[66:81], v[228:231], v[102:105], v[66:81]
	s_waitcnt lgkmcnt(1)
	v_mfma_f32_32x32x16_bf16 v[66:81], v[232:235], v[106:109], v[66:81]
	s_waitcnt lgkmcnt(0)
	v_mfma_f32_32x32x16_bf16 v[66:81], v[236:239], v[110:113], v[66:81]
	v_lshl_add_u32 v178, v197, 2, v147
	ds_read_b32 v179, v178 offset:256
	ds_read_b32 v177, v178 offset:260
	ds_read_b32 v198, v178 offset:264
	ds_read_b32 v197, v178 offset:268
	ds_read_b32 v200, v178 offset:288
	ds_read_b32 v199, v178 offset:292
	ds_read_b32 v202, v178 offset:296
	ds_read_b32 v201, v178 offset:300
	s_waitcnt lgkmcnt(4)
	ds_read_b32 v215, v178 offset:320
	ds_read_b32 v203, v178 offset:324
	ds_read_b32 v217, v178 offset:328
	ds_read_b32 v216, v178 offset:332
	ds_read_b32 v219, v178 offset:352
	ds_read_b32 v218, v178 offset:356
	ds_read_b32 v221, v178 offset:360
	ds_read_b32 v220, v178 offset:364
	s_waitcnt lgkmcnt(0)
	v_fmac_f32_e32 v179, 0x3e0293ee, v66
	v_fmac_f32_e32 v177, 0x3e0293ee, v67
	v_max3_f32 v66, v179, s15, v177
	v_fmac_f32_e32 v198, 0x3e0293ee, v68
	v_fmac_f32_e32 v197, 0x3e0293ee, v69
	v_max3_f32 v66, v66, v198, v197
	v_fmac_f32_e32 v200, 0x3e0293ee, v70
	v_fmac_f32_e32 v199, 0x3e0293ee, v71
	v_max3_f32 v66, v66, v200, v199
	v_fmac_f32_e32 v202, 0x3e0293ee, v72
	v_fmac_f32_e32 v201, 0x3e0293ee, v73
	v_max3_f32 v66, v66, v202, v201
	v_fmac_f32_e32 v215, 0x3e0293ee, v74
	v_fmac_f32_e32 v203, 0x3e0293ee, v75
	v_and_b32_e32 v68, 64, v208
	v_max3_f32 v66, v66, v215, v203
	v_fmac_f32_e32 v217, 0x3e0293ee, v76
	v_fmac_f32_e32 v216, 0x3e0293ee, v77
	v_xor_b32_e32 v67, 32, v208
	v_add_u32_e32 v68, 64, v68
	v_max3_f32 v66, v66, v217, v216
	v_fmac_f32_e32 v219, 0x3e0293ee, v78
	v_fmac_f32_e32 v218, 0x3e0293ee, v79
	v_cmp_lt_i32_e32 vcc, v67, v68
	v_max3_f32 v66, v66, v219, v218
	v_fmac_f32_e32 v221, 0x3e0293ee, v80
	v_cndmask_b32_e32 v67, v208, v67, vcc
	v_fmac_f32_e32 v220, 0x3e0293ee, v81
	v_lshlrev_b32_e32 v67, 2, v67
	v_max3_f32 v66, v66, v221, v220
	ds_bpermute_b32 v67, v67, v66
	s_waitcnt lgkmcnt(0)
	v_max3_f32 v66, v193, v66, v67
	v_cmp_gt_f32_e32 vcc, v66, v193
	s_cbranch_vccz .LBB0_208
	v_sub_f32_e32 v67, v193, v66
	v_exp_f32_e32 v68, v67
	v_mov_b32_e32 v193, v66
	v_mul_f32_e32 v194, v194, v68
	v_pk_mul_f32 v[64:65], v[64:65], v[68:69] op_sel_hi:[1,0]
	v_pk_mul_f32 v[62:63], v[62:63], v[68:69] op_sel_hi:[1,0]
	v_pk_mul_f32 v[60:61], v[60:61], v[68:69] op_sel_hi:[1,0]
	v_pk_mul_f32 v[58:59], v[58:59], v[68:69] op_sel_hi:[1,0]
	v_pk_mul_f32 v[56:57], v[56:57], v[68:69] op_sel_hi:[1,0]
	v_pk_mul_f32 v[54:55], v[54:55], v[68:69] op_sel_hi:[1,0]
	v_pk_mul_f32 v[52:53], v[52:53], v[68:69] op_sel_hi:[1,0]
	v_pk_mul_f32 v[50:51], v[50:51], v[68:69] op_sel_hi:[1,0]
	v_pk_mul_f32 v[48:49], v[48:49], v[68:69] op_sel_hi:[1,0]
	v_pk_mul_f32 v[46:47], v[46:47], v[68:69] op_sel_hi:[1,0]
	v_pk_mul_f32 v[44:45], v[44:45], v[68:69] op_sel_hi:[1,0]
	v_pk_mul_f32 v[42:43], v[42:43], v[68:69] op_sel_hi:[1,0]
	v_pk_mul_f32 v[40:41], v[40:41], v[68:69] op_sel_hi:[1,0]
	v_pk_mul_f32 v[38:39], v[38:39], v[68:69] op_sel_hi:[1,0]
	v_pk_mul_f32 v[36:37], v[36:37], v[68:69] op_sel_hi:[1,0]
	v_pk_mul_f32 v[34:35], v[34:35], v[68:69] op_sel_hi:[1,0]
	v_pk_mul_f32 v[32:33], v[32:33], v[68:69] op_sel_hi:[1,0]
	v_pk_mul_f32 v[30:31], v[30:31], v[68:69] op_sel_hi:[1,0]
	v_pk_mul_f32 v[28:29], v[28:29], v[68:69] op_sel_hi:[1,0]
	v_pk_mul_f32 v[26:27], v[26:27], v[68:69] op_sel_hi:[1,0]
	v_pk_mul_f32 v[24:25], v[24:25], v[68:69] op_sel_hi:[1,0]
	v_pk_mul_f32 v[22:23], v[22:23], v[68:69] op_sel_hi:[1,0]
	v_pk_mul_f32 v[20:21], v[20:21], v[68:69] op_sel_hi:[1,0]
	v_pk_mul_f32 v[18:19], v[18:19], v[68:69] op_sel_hi:[1,0]
	v_pk_mul_f32 v[16:17], v[16:17], v[68:69] op_sel_hi:[1,0]
	v_pk_mul_f32 v[14:15], v[14:15], v[68:69] op_sel_hi:[1,0]
	v_pk_mul_f32 v[12:13], v[12:13], v[68:69] op_sel_hi:[1,0]
	v_pk_mul_f32 v[10:11], v[10:11], v[68:69] op_sel_hi:[1,0]
	v_pk_mul_f32 v[8:9], v[8:9], v[68:69] op_sel_hi:[1,0]
	v_pk_mul_f32 v[6:7], v[6:7], v[68:69] op_sel_hi:[1,0]
	v_pk_mul_f32 v[4:5], v[4:5], v[68:69] op_sel_hi:[1,0]
	v_pk_mul_f32 v[2:3], v[2:3], v[68:69] op_sel_hi:[1,0]

; #define LAS __attribute__((address_space(3)))
; #define MFMA32(a, b, c) __builtin_amdgcn_mfma_f32_32x32x16_bf16((a), (b), (c), 0, 0, 0)
; template <int D, int NM, int KSTR, int VSTR, bool QLDS, class BF> ...
;     v8s P[NM][2];
; #pragma unroll
;     for (int m = 0; m < NM; ++m) {
;         const LAS unsigned char* Kb = (m == 0 ? K0 : K1) + (32 * kk + r) * KSTR + h * 16;
;         v16f S;
; #pragma unroll
;         for (int i = 0; i < 16; ++i) S[i] = 0.f;
;         v8s kfa[D / 16];
; #pragma unroll
;         for (int ks = 0; ks < D / 16; ++ks) kfa[ks] = *(const LAS v8s*)(Kb + ks * 32);
;         __builtin_amdgcn_sched_barrier(0);
; #pragma unroll
;         for (int ks = 0; ks < D / 16; ++ks) { const v8s qf = QLDS ? *(const LAS v8s*)(qlds + (m * (D / 16) + ks) * 1024) : Q[m][ks]; S = MFMA32(kfa[ks], qf, S); }
;         __builtin_amdgcn_sched_barrier(0);
;         float tmax = NEGBIG;
; #pragma unroll
;         for (int i = 0; i < 16; ++i) { S[i] = S[i] * c1 + bias(i); tmax = fmaxf(tmax, S[i]); }
; __device__ __forceinline__ void dil_item(const Params& p, LAS unsigned char* lds, const int bitem) {
;     ...
;             for (int kk = 0; kk < 2; ++kk) {
;                 const int js = j0 + 32 * kk;
;                 if (js + 31 >= jq0 - 64 && js <= jq0 + 31 + 64) {
;                     const BiasBand bf{tab, js + 4 * h - jq};
;                     attn_subtile<128, 1, 272, 320, false>(base + DL_K, base + DL_K, base + DL_VT, kk, Q, nullptr, st, c1, bf, r, h);
.LBB0_209:
	s_or_b64 exec, exec, s[20:21]
	v_subrev_u32_e32 v66, 32, v176
	v_add_u32_e32 v67, -1, v176
	v_cmp_ge_i32_e32 vcc, v67, v188
	v_cmp_le_i32_e64 s[38:39], v66, v189
	s_and_b64 s[10:11], vcc, s[38:39]
	s_and_saveexec_b64 s[20:21], s[10:11]
	s_cbranch_execz .LBB0_164
	v_add_u32_e32 v70, v190, v187
	ds_read_b128 v[66:69], v70 offset:8704
	ds_read_b128 v[198:201], v70 offset:8736
	ds_read_b128 v[216:219], v70 offset:8768
	ds_read_b128 v[220:223], v70 offset:8800
	ds_read_b128 v[224:227], v70 offset:8832
	ds_read_b128 v[228:231], v70 offset:8864
	ds_read_b128 v[232:235], v70 offset:8896
	ds_read_b128 v[236:239], v70 offset:8928
	v_lshl_add_u64 v[176:177], v[174:175], 0, s[6:7]
	v_subrev_u32_e32 v179, 32, v176
	s_waitcnt lgkmcnt(7)
	v_mfma_f32_32x32x16_bf16 v[66:81], v[66:69], v[82:85], 0
	s_waitcnt lgkmcnt(6)
	v_mfma_f32_32x32x16_bf16 v[66:81], v[198:201], v[86:89], v[66:81]
	s_waitcnt lgkmcnt(5)
	v_mfma_f32_32x32x16_bf16 v[66:81], v[216:219], v[90:93], v[66:81]
	s_waitcnt lgkmcnt(4)
	v_mfma_f32_32x32x16_bf16 v[66:81], v[220:223], v[94:97], v[66:81]
	s_waitcnt lgkmcnt(3)
	v_mfma_f32_32x32x16_bf16 v[66:81], v[224:227], v[98:101], v[66:81]
	s_waitcnt lgkmcnt(2)
	v_mfma_f32_32x32x16_bf16 v[66:81], v[228:231], v[102:105], v[66:81]
	s_waitcnt lgkmcnt(1)
	v_mfma_f32_32x32x16_bf16 v[66:81], v[232:235], v[106:109], v[66:81]
	s_waitcnt lgkmcnt(0)
	v_mfma_f32_32x32x16_bf16 v[66:81], v[236:239], v[110:113], v[66:81]
	v_lshl_add_u32 v176, v179, 2, v147
	ds_read_b32 v178, v176 offset:256
	ds_read_b32 v177, v176 offset:260
	ds_read_b32 v197, v176 offset:264
	ds_read_b32 v179, v176 offset:268
	ds_read_b32 v199, v176 offset:288
	ds_read_b32 v198, v176 offset:292
	ds_read_b32 v201, v176 offset:296
	ds_read_b32 v200, v176 offset:300
	s_waitcnt lgkmcnt(4)
	ds_read_b32 v203, v176 offset:320
	ds_read_b32 v202, v176 offset:324
	ds_read_b32 v216, v176 offset:328
	ds_read_b32 v215, v176 offset:332
	ds_read_b32 v218, v176 offset:352
	ds_read_b32 v217, v176 offset:356
	ds_read_b32 v220, v176 offset:360
	ds_read_b32 v219, v176 offset:364
	s_waitcnt lgkmcnt(0)
	v_fmac_f32_e32 v178, 0x3e0293ee, v66
	v_fmac_f32_e32 v177, 0x3e0293ee, v67
	v_max3_f32 v66, v178, s15, v177
	v_fmac_f32_e32 v197, 0x3e0293ee, v68
	v_fmac_f32_e32 v179, 0x3e0293ee, v69
	v_max3_f32 v66, v66, v197, v179
	v_fmac_f32_e32 v199, 0x3e0293ee, v70
	v_fmac_f32_e32 v198, 0x3e0293ee, v71
	v_max3_f32 v66, v66, v199, v198
	v_fmac_f32_e32 v201, 0x3e0293ee, v72
	v_fmac_f32_e32 v200, 0x3e0293ee, v73
	v_max3_f32 v66, v66, v201, v200
	v_fmac_f32_e32 v203, 0x3e0293ee, v74
	v_fmac_f32_e32 v202, 0x3e0293ee, v75
	v_and_b32_e32 v68, 64, v208
	v_max3_f32 v66, v66, v203, v202
	v_fmac_f32_e32 v216, 0x3e0293ee, v76
	v_fmac_f32_e32 v215, 0x3e0293ee, v77
	v_xor_b32_e32 v67, 32, v208
	v_add_u32_e32 v68, 64, v68
	v_max3_f32 v66, v66, v216, v215
	v_fmac_f32_e32 v218, 0x3e0293ee, v78
	v_fmac_f32_e32 v217, 0x3e0293ee, v79
	v_cmp_lt_i32_e32 vcc, v67, v68
	v_max3_f32 v66, v66, v218, v217
	v_fmac_f32_e32 v220, 0x3e0293ee, v80
	v_cndmask_b32_e32 v67, v208, v67, vcc
	v_fmac_f32_e32 v219, 0x3e0293ee, v81
	v_lshlrev_b32_e32 v67, 2, v67
	v_max3_f32 v66, v66, v220, v219
	ds_bpermute_b32 v67, v67, v66
	s_waitcnt lgkmcnt(0)
	v_max3_f32 v66, v193, v66, v67
	v_cmp_gt_f32_e32 vcc, v66, v193
	s_cbranch_vccz .LBB0_163
	v_sub_f32_e32 v67, v193, v66
	v_exp_f32_e32 v68, v67
	v_mov_b32_e32 v193, v66
	v_mul_f32_e32 v194, v194, v68
	v_pk_mul_f32 v[64:65], v[64:65], v[68:69] op_sel_hi:[1,0]
	v_pk_mul_f32 v[62:63], v[62:63], v[68:69] op_sel_hi:[1,0]
	v_pk_mul_f32 v[60:61], v[60:61], v[68:69] op_sel_hi:[1,0]
	v_pk_mul_f32 v[58:59], v[58:59], v[68:69] op_sel_hi:[1,0]
	v_pk_mul_f32 v[56:57], v[56:57], v[68:69] op_sel_hi:[1,0]
	v_pk_mul_f32 v[54:55], v[54:55], v[68:69] op_sel_hi:[1,0]
	v_pk_mul_f32 v[52:53], v[52:53], v[68:69] op_sel_hi:[1,0]
	v_pk_mul_f32 v[50:51], v[50:51], v[68:69] op_sel_hi:[1,0]
	v_pk_mul_f32 v[48:49], v[48:49], v[68:69] op_sel_hi:[1,0]
	v_pk_mul_f32 v[46:47], v[46:47], v[68:69] op_sel_hi:[1,0]
	v_pk_mul_f32 v[44:45], v[44:45], v[68:69] op_sel_hi:[1,0]
	v_pk_mul_f32 v[42:43], v[42:43], v[68:69] op_sel_hi:[1,0]
	v_pk_mul_f32 v[40:41], v[40:41], v[68:69] op_sel_hi:[1,0]
	v_pk_mul_f32 v[38:39], v[38:39], v[68:69] op_sel_hi:[1,0]
	v_pk_mul_f32 v[36:37], v[36:37], v[68:69] op_sel_hi:[1,0]
	v_pk_mul_f32 v[34:35], v[34:35], v[68:69] op_sel_hi:[1,0]
	v_pk_mul_f32 v[32:33], v[32:33], v[68:69] op_sel_hi:[1,0]
	v_pk_mul_f32 v[30:31], v[30:31], v[68:69] op_sel_hi:[1,0]
	v_pk_mul_f32 v[28:29], v[28:29], v[68:69] op_sel_hi:[1,0]
	v_pk_mul_f32 v[26:27], v[26:27], v[68:69] op_sel_hi:[1,0]
	v_pk_mul_f32 v[24:25], v[24:25], v[68:69] op_sel_hi:[1,0]
	v_pk_mul_f32 v[22:23], v[22:23], v[68:69] op_sel_hi:[1,0]
	v_pk_mul_f32 v[20:21], v[20:21], v[68:69] op_sel_hi:[1,0]
	v_pk_mul_f32 v[18:19], v[18:19], v[68:69] op_sel_hi:[1,0]
	v_pk_mul_f32 v[16:17], v[16:17], v[68:69] op_sel_hi:[1,0]
	v_pk_mul_f32 v[14:15], v[14:15], v[68:69] op_sel_hi:[1,0]
	v_pk_mul_f32 v[12:13], v[12:13], v[68:69] op_sel_hi:[1,0]
	v_pk_mul_f32 v[10:11], v[10:11], v[68:69] op_sel_hi:[1,0]
	v_pk_mul_f32 v[8:9], v[8:9], v[68:69] op_sel_hi:[1,0]
	v_pk_mul_f32 v[6:7], v[6:7], v[68:69] op_sel_hi:[1,0]
	v_pk_mul_f32 v[4:5], v[4:5], v[68:69] op_sel_hi:[1,0]
	v_pk_mul_f32 v[2:3], v[2:3], v[68:69] op_sel_hi:[1,0]
	s_branch .LBB0_163
